# v49 + split-K partial stores write-through (sc1) and no L2 writeback (buffer_wbl2) before the arrive counters of the sample-row mini units
# baseline (speedup 1.0000x reference)
.LBB0_585:
	s_and_b64 vcc, exec, s[26:27]
	s_cbranch_vccz .LBB0_591
	v_lshl_add_u64 v[66:67], v[162:163], 0, v[174:175]
	global_load_dwordx2 v[68:69], v[66:67], off
	s_add_i32 s8, s8, s56
	s_lshl_b64 s[26:27], s[8:9], 20
	s_add_u32 vcc_lo, s4, s26
	s_addc_u32 vcc_hi, s5, s27
	v_lshl_add_u64 v[70:71], vcc, 0, v[154:155]
	v_lshlrev_b64 v[64:65], 2, v[174:175]
	v_lshl_add_u64 v[70:71], v[70:71], 0, v[64:65]
	s_waitcnt vmcnt(0)
	v_cvt_f32_ubyte3_e32 v73, v68
	v_cvt_f32_ubyte2_e32 v72, v68
	v_cvt_f32_ubyte1_e32 v75, v68
	v_cvt_f32_ubyte0_e32 v74, v68
	v_pk_mul_f32 v[74:75], v[74:75], s[74:75] op_sel_hi:[1,0]
	v_pk_mul_f32 v[72:73], v[72:73], s[74:75] op_sel_hi:[1,0]
	v_pk_mul_f32 v[60:61], v[60:61], v[74:75]
	v_pk_mul_f32 v[62:63], v[62:63], v[72:73]
	global_store_dwordx4 v[70:71], v[60:63], off sc1
	s_nop 1
	v_cvt_f32_ubyte3_e32 v61, v69
	v_cvt_f32_ubyte2_e32 v60, v69
	v_cvt_f32_ubyte1_e32 v63, v69
	v_cvt_f32_ubyte0_e32 v62, v69
	v_pk_mul_f32 v[62:63], v[62:63], s[74:75] op_sel_hi:[1,0]
	v_pk_mul_f32 v[60:61], v[60:61], s[74:75] op_sel_hi:[1,0]
	v_pk_mul_f32 v[56:57], v[56:57], v[62:63]
	v_pk_mul_f32 v[58:59], v[58:59], v[60:61]
	global_store_dwordx4 v[70:71], v[56:59], off offset:16 sc1
	global_load_dwordx2 v[56:57], v[66:67], off offset:128
	s_waitcnt vmcnt(0)
	v_cvt_f32_ubyte1_e32 v61, v56
	v_cvt_f32_ubyte3_e32 v59, v56
	v_cvt_f32_ubyte2_e32 v58, v56
	v_cvt_f32_ubyte0_e32 v60, v56
	v_pk_mul_f32 v[60:61], v[60:61], s[74:75] op_sel_hi:[1,0]
	v_pk_mul_f32 v[58:59], v[58:59], s[74:75] op_sel_hi:[1,0]
	v_pk_mul_f32 v[52:53], v[52:53], v[60:61]
	v_pk_mul_f32 v[54:55], v[54:55], v[58:59]
	global_store_dwordx4 v[70:71], v[52:55], off offset:512 sc1
	s_nop 1
	v_cvt_f32_ubyte3_e32 v53, v57
	v_cvt_f32_ubyte2_e32 v52, v57
	v_cvt_f32_ubyte1_e32 v55, v57
	v_cvt_f32_ubyte0_e32 v54, v57
	v_pk_mul_f32 v[54:55], v[54:55], s[74:75] op_sel_hi:[1,0]
	v_pk_mul_f32 v[52:53], v[52:53], s[74:75] op_sel_hi:[1,0]
	v_pk_mul_f32 v[48:49], v[48:49], v[54:55]
	v_pk_mul_f32 v[50:51], v[50:51], v[52:53]
	global_store_dwordx4 v[70:71], v[48:51], off offset:528 sc1
	v_lshl_add_u64 v[52:53], vcc, 0, v[156:157]
	v_lshl_add_u64 v[52:53], v[52:53], 0, v[64:65]
	v_lshl_add_u64 v[48:49], v[164:165], 0, v[174:175]
	global_load_dwordx2 v[50:51], v[48:49], off
	s_waitcnt vmcnt(0)
	v_cvt_f32_ubyte3_e32 v55, v50
	v_cvt_f32_ubyte2_e32 v54, v50
	v_cvt_f32_ubyte1_e32 v57, v50
	v_cvt_f32_ubyte0_e32 v56, v50
	v_pk_mul_f32 v[56:57], v[56:57], s[74:75] op_sel_hi:[1,0]
	v_pk_mul_f32 v[54:55], v[54:55], s[74:75] op_sel_hi:[1,0]
	v_pk_mul_f32 v[44:45], v[44:45], v[56:57]
	v_pk_mul_f32 v[46:47], v[46:47], v[54:55]
	global_store_dwordx4 v[52:53], v[44:47], off sc1
	s_nop 1
	v_cvt_f32_ubyte3_e32 v45, v51
	v_cvt_f32_ubyte2_e32 v44, v51
	v_cvt_f32_ubyte1_e32 v47, v51
	v_cvt_f32_ubyte0_e32 v46, v51
	v_pk_mul_f32 v[46:47], v[46:47], s[74:75] op_sel_hi:[1,0]
	v_pk_mul_f32 v[44:45], v[44:45], s[74:75] op_sel_hi:[1,0]
	v_pk_mul_f32 v[40:41], v[40:41], v[46:47]
	v_pk_mul_f32 v[42:43], v[42:43], v[44:45]
	global_store_dwordx4 v[52:53], v[40:43], off offset:16 sc1
	global_load_dwordx2 v[40:41], v[48:49], off offset:128
	s_waitcnt vmcnt(0)
	v_cvt_f32_ubyte1_e32 v45, v40
	v_cvt_f32_ubyte3_e32 v43, v40
	v_cvt_f32_ubyte2_e32 v42, v40
	v_cvt_f32_ubyte0_e32 v44, v40
	v_pk_mul_f32 v[44:45], v[44:45], s[74:75] op_sel_hi:[1,0]
	v_pk_mul_f32 v[42:43], v[42:43], s[74:75] op_sel_hi:[1,0]
	v_pk_mul_f32 v[36:37], v[36:37], v[44:45]
	v_pk_mul_f32 v[38:39], v[38:39], v[42:43]
	global_store_dwordx4 v[52:53], v[36:39], off offset:512 sc1
	s_nop 1
	v_cvt_f32_ubyte3_e32 v37, v41
	v_cvt_f32_ubyte2_e32 v36, v41
	v_cvt_f32_ubyte1_e32 v39, v41
	v_cvt_f32_ubyte0_e32 v38, v41
	v_pk_mul_f32 v[38:39], v[38:39], s[74:75] op_sel_hi:[1,0]
	v_pk_mul_f32 v[36:37], v[36:37], s[74:75] op_sel_hi:[1,0]
	v_pk_mul_f32 v[32:33], v[32:33], v[38:39]
	v_pk_mul_f32 v[34:35], v[34:35], v[36:37]
	global_store_dwordx4 v[52:53], v[32:35], off offset:528 sc1
	v_lshl_add_u64 v[36:37], vcc, 0, v[158:159]
	v_lshl_add_u64 v[36:37], v[36:37], 0, v[64:65]
	v_lshl_add_u64 v[32:33], v[166:167], 0, v[174:175]
	global_load_dwordx2 v[34:35], v[32:33], off
	s_waitcnt vmcnt(0)
	v_cvt_f32_ubyte3_e32 v39, v34
	v_cvt_f32_ubyte2_e32 v38, v34
	v_cvt_f32_ubyte1_e32 v41, v34
	v_cvt_f32_ubyte0_e32 v40, v34
	v_pk_mul_f32 v[40:41], v[40:41], s[74:75] op_sel_hi:[1,0]
	v_pk_mul_f32 v[38:39], v[38:39], s[74:75] op_sel_hi:[1,0]
	v_pk_mul_f32 v[28:29], v[28:29], v[40:41]
	v_pk_mul_f32 v[30:31], v[30:31], v[38:39]
	global_store_dwordx4 v[36:37], v[28:31], off sc1
	s_nop 1
	v_cvt_f32_ubyte3_e32 v29, v35
	v_cvt_f32_ubyte2_e32 v28, v35
	v_cvt_f32_ubyte1_e32 v31, v35
	v_cvt_f32_ubyte0_e32 v30, v35
	v_pk_mul_f32 v[30:31], v[30:31], s[74:75] op_sel_hi:[1,0]
	v_pk_mul_f32 v[28:29], v[28:29], s[74:75] op_sel_hi:[1,0]
	v_pk_mul_f32 v[24:25], v[24:25], v[30:31]
	v_pk_mul_f32 v[26:27], v[26:27], v[28:29]
	global_store_dwordx4 v[36:37], v[24:27], off offset:16 sc1
	global_load_dwordx2 v[24:25], v[32:33], off offset:128
	s_waitcnt vmcnt(0)
	v_cvt_f32_ubyte1_e32 v29, v24
	v_cvt_f32_ubyte3_e32 v27, v24
	v_cvt_f32_ubyte2_e32 v26, v24
	v_cvt_f32_ubyte0_e32 v28, v24
	v_pk_mul_f32 v[28:29], v[28:29], s[74:75] op_sel_hi:[1,0]
	v_pk_mul_f32 v[26:27], v[26:27], s[74:75] op_sel_hi:[1,0]
	v_pk_mul_f32 v[20:21], v[20:21], v[28:29]
	v_pk_mul_f32 v[22:23], v[22:23], v[26:27]
	global_store_dwordx4 v[36:37], v[20:23], off offset:512 sc1
	s_nop 1
	v_cvt_f32_ubyte3_e32 v21, v25
	v_cvt_f32_ubyte2_e32 v20, v25
	v_cvt_f32_ubyte1_e32 v23, v25
	v_cvt_f32_ubyte0_e32 v22, v25
	v_pk_mul_f32 v[22:23], v[22:23], s[74:75] op_sel_hi:[1,0]
	v_pk_mul_f32 v[20:21], v[20:21], s[74:75] op_sel_hi:[1,0]
	v_pk_mul_f32 v[16:17], v[16:17], v[22:23]
	v_pk_mul_f32 v[18:19], v[18:19], v[20:21]
	global_store_dwordx4 v[36:37], v[16:19], off offset:528 sc1
	v_lshl_add_u64 v[20:21], vcc, 0, v[160:161]
	v_lshl_add_u64 v[20:21], v[20:21], 0, v[64:65]
	v_lshl_add_u64 v[16:17], v[168:169], 0, v[174:175]
	global_load_dwordx2 v[18:19], v[16:17], off
	s_waitcnt vmcnt(0)
	v_cvt_f32_ubyte3_e32 v23, v18
	v_cvt_f32_ubyte2_e32 v22, v18
	v_cvt_f32_ubyte1_e32 v25, v18
	v_cvt_f32_ubyte0_e32 v24, v18
	v_pk_mul_f32 v[24:25], v[24:25], s[74:75] op_sel_hi:[1,0]
	v_pk_mul_f32 v[22:23], v[22:23], s[74:75] op_sel_hi:[1,0]
	v_pk_mul_f32 v[12:13], v[12:13], v[24:25]
	v_pk_mul_f32 v[14:15], v[14:15], v[22:23]
	global_store_dwordx4 v[20:21], v[12:15], off sc1
	s_nop 1
	v_cvt_f32_ubyte3_e32 v13, v19
	v_cvt_f32_ubyte2_e32 v12, v19
	v_cvt_f32_ubyte1_e32 v15, v19
	v_cvt_f32_ubyte0_e32 v14, v19
	v_pk_mul_f32 v[14:15], v[14:15], s[74:75] op_sel_hi:[1,0]
	v_pk_mul_f32 v[12:13], v[12:13], s[74:75] op_sel_hi:[1,0]
	v_pk_mul_f32 v[8:9], v[8:9], v[14:15]
	v_pk_mul_f32 v[10:11], v[10:11], v[12:13]
	global_store_dwordx4 v[20:21], v[8:11], off offset:16 sc1
	global_load_dwordx2 v[8:9], v[16:17], off offset:128
	s_waitcnt vmcnt(0)
	v_cvt_f32_ubyte1_e32 v13, v8
	v_cvt_f32_ubyte3_e32 v11, v8
	v_cvt_f32_ubyte2_e32 v10, v8
	v_cvt_f32_ubyte0_e32 v12, v8
	v_pk_mul_f32 v[12:13], v[12:13], s[74:75] op_sel_hi:[1,0]
	v_pk_mul_f32 v[10:11], v[10:11], s[74:75] op_sel_hi:[1,0]
	v_pk_mul_f32 v[4:5], v[4:5], v[12:13]
	v_pk_mul_f32 v[6:7], v[6:7], v[10:11]
	global_store_dwordx4 v[20:21], v[4:7], off offset:512 sc1
	s_nop 1
	v_cvt_f32_ubyte3_e32 v5, v9
	v_cvt_f32_ubyte2_e32 v4, v9
	v_cvt_f32_ubyte1_e32 v7, v9
	v_cvt_f32_ubyte0_e32 v6, v9
	v_pk_mul_f32 v[6:7], v[6:7], s[74:75] op_sel_hi:[1,0]
	v_pk_mul_f32 v[4:5], v[4:5], s[74:75] op_sel_hi:[1,0]
	v_pk_mul_f32 v[0:1], v[0:1], v[6:7]
	v_pk_mul_f32 v[2:3], v[2:3], v[4:5]
	global_store_dwordx4 v[20:21], v[0:3], off offset:528 sc1
	s_waitcnt vmcnt(0)
	s_barrier
	s_and_saveexec_b64 s[26:27], s[18:19]
	s_cbranch_execz .LBB0_588
	s_lshl_b32 s34, s10, 6
	s_ashr_i32 s35, s34, 31
	s_lshl_b64 s[34:35], s[34:35], 2
	s_add_u32 s34, s75, s34
	s_addc_u32 s35, s21, s35
	s_waitcnt vmcnt(0)
	s_waitcnt vmcnt(0)
	v_mov_b64_e32 v[0:1], s[34:35]
	flat_atomic_add v0, v[0:1], v182 sc0
	s_waitcnt vmcnt(0) lgkmcnt(0)
	ds_write_b32 v145, v0
	v_mov_b64_e32 v[2:3], s[34:35]

.LBB0_692:
	s_and_b64 vcc, exec, s[8:9]
	s_cbranch_vccz .LBB0_698
	s_lshl_b32 s86, s91, 11
	s_ashr_i32 s87, s86, 31
	v_lshl_add_u64 v[64:65], v[146:147], 0, s[86:87]
	v_lshl_add_u64 v[66:67], v[64:65], 0, v[158:159]
	global_load_dwordx2 v[68:69], v[66:67], off
	s_lshl_b32 s8, s91, 2
	s_add_i32 s8, s8, s90
	s_ashr_i32 s9, s8, 31
	s_lshl_b64 s[8:9], s[8:9], 20
	s_add_u32 s8, s4, s8
	s_addc_u32 s9, s5, s9
	v_lshl_add_u64 v[70:71], s[8:9], 0, v[138:139]
	v_lshlrev_b64 v[64:65], 2, v[158:159]
	v_lshl_add_u64 v[70:71], v[70:71], 0, v[64:65]
	s_waitcnt vmcnt(0)
	v_cvt_f32_ubyte3_e32 v73, v68
	v_cvt_f32_ubyte2_e32 v72, v68
	v_cvt_f32_ubyte1_e32 v75, v68
	v_cvt_f32_ubyte0_e32 v74, v68
	v_pk_mul_f32 v[74:75], v[74:75], s[74:75] op_sel_hi:[1,0]
	v_pk_mul_f32 v[72:73], v[72:73], s[74:75] op_sel_hi:[1,0]
	v_pk_mul_f32 v[60:61], v[60:61], v[74:75]
	v_pk_mul_f32 v[62:63], v[62:63], v[72:73]
	global_store_dwordx4 v[70:71], v[60:63], off sc1
	s_nop 1
	v_cvt_f32_ubyte3_e32 v61, v69
	v_cvt_f32_ubyte2_e32 v60, v69
	v_cvt_f32_ubyte1_e32 v63, v69
	v_cvt_f32_ubyte0_e32 v62, v69
	v_pk_mul_f32 v[62:63], v[62:63], s[74:75] op_sel_hi:[1,0]
	v_pk_mul_f32 v[60:61], v[60:61], s[74:75] op_sel_hi:[1,0]
	v_pk_mul_f32 v[56:57], v[56:57], v[62:63]
	v_pk_mul_f32 v[58:59], v[58:59], v[60:61]
	global_store_dwordx4 v[70:71], v[56:59], off offset:16 sc1
	global_load_dwordx2 v[56:57], v[66:67], off offset:128
	s_waitcnt vmcnt(0)
	v_cvt_f32_ubyte1_e32 v61, v56
	v_cvt_f32_ubyte3_e32 v59, v56
	v_cvt_f32_ubyte2_e32 v58, v56
	v_cvt_f32_ubyte0_e32 v60, v56
	v_pk_mul_f32 v[60:61], v[60:61], s[74:75] op_sel_hi:[1,0]
	v_pk_mul_f32 v[58:59], v[58:59], s[74:75] op_sel_hi:[1,0]
	v_pk_mul_f32 v[52:53], v[52:53], v[60:61]
	v_pk_mul_f32 v[54:55], v[54:55], v[58:59]
	global_store_dwordx4 v[70:71], v[52:55], off offset:512 sc1
	s_nop 1
	v_cvt_f32_ubyte3_e32 v53, v57
	v_cvt_f32_ubyte2_e32 v52, v57
	v_cvt_f32_ubyte1_e32 v55, v57
	v_cvt_f32_ubyte0_e32 v54, v57
	v_pk_mul_f32 v[54:55], v[54:55], s[74:75] op_sel_hi:[1,0]
	v_pk_mul_f32 v[52:53], v[52:53], s[74:75] op_sel_hi:[1,0]
	v_pk_mul_f32 v[48:49], v[48:49], v[54:55]
	v_pk_mul_f32 v[50:51], v[50:51], v[52:53]
	global_store_dwordx4 v[70:71], v[48:51], off offset:528 sc1
	v_lshl_add_u64 v[52:53], s[8:9], 0, v[140:141]
	v_lshl_add_u64 v[52:53], v[52:53], 0, v[64:65]
	v_lshl_add_u64 v[48:49], v[148:149], 0, s[86:87]
	v_lshl_add_u64 v[48:49], v[48:49], 0, v[158:159]
	global_load_dwordx2 v[50:51], v[48:49], off
	s_waitcnt vmcnt(0)
	v_cvt_f32_ubyte3_e32 v55, v50
	v_cvt_f32_ubyte2_e32 v54, v50
	v_cvt_f32_ubyte1_e32 v57, v50
	v_cvt_f32_ubyte0_e32 v56, v50
	v_pk_mul_f32 v[56:57], v[56:57], s[74:75] op_sel_hi:[1,0]
	v_pk_mul_f32 v[54:55], v[54:55], s[74:75] op_sel_hi:[1,0]
	v_pk_mul_f32 v[44:45], v[44:45], v[56:57]
	v_pk_mul_f32 v[46:47], v[46:47], v[54:55]
	global_store_dwordx4 v[52:53], v[44:47], off sc1
	s_nop 1
	v_cvt_f32_ubyte3_e32 v45, v51
	v_cvt_f32_ubyte2_e32 v44, v51
	v_cvt_f32_ubyte1_e32 v47, v51
	v_cvt_f32_ubyte0_e32 v46, v51
	v_pk_mul_f32 v[46:47], v[46:47], s[74:75] op_sel_hi:[1,0]
	v_pk_mul_f32 v[44:45], v[44:45], s[74:75] op_sel_hi:[1,0]
	v_pk_mul_f32 v[40:41], v[40:41], v[46:47]
	v_pk_mul_f32 v[42:43], v[42:43], v[44:45]
	global_store_dwordx4 v[52:53], v[40:43], off offset:16 sc1
	global_load_dwordx2 v[40:41], v[48:49], off offset:128
	s_waitcnt vmcnt(0)
	v_cvt_f32_ubyte1_e32 v45, v40
	v_cvt_f32_ubyte3_e32 v43, v40
	v_cvt_f32_ubyte2_e32 v42, v40
	v_cvt_f32_ubyte0_e32 v44, v40
	v_pk_mul_f32 v[44:45], v[44:45], s[74:75] op_sel_hi:[1,0]
	v_pk_mul_f32 v[42:43], v[42:43], s[74:75] op_sel_hi:[1,0]
	v_pk_mul_f32 v[36:37], v[36:37], v[44:45]
	v_pk_mul_f32 v[38:39], v[38:39], v[42:43]
	global_store_dwordx4 v[52:53], v[36:39], off offset:512 sc1
	s_nop 1
	v_cvt_f32_ubyte3_e32 v37, v41
	v_cvt_f32_ubyte2_e32 v36, v41
	v_cvt_f32_ubyte1_e32 v39, v41
	v_cvt_f32_ubyte0_e32 v38, v41
	v_pk_mul_f32 v[38:39], v[38:39], s[74:75] op_sel_hi:[1,0]
	v_pk_mul_f32 v[36:37], v[36:37], s[74:75] op_sel_hi:[1,0]
	v_pk_mul_f32 v[32:33], v[32:33], v[38:39]
	v_pk_mul_f32 v[34:35], v[34:35], v[36:37]
	global_store_dwordx4 v[52:53], v[32:35], off offset:528 sc1
	v_lshl_add_u64 v[36:37], s[8:9], 0, v[142:143]
	v_lshl_add_u64 v[36:37], v[36:37], 0, v[64:65]
	v_lshl_add_u64 v[32:33], v[150:151], 0, s[86:87]
	v_lshl_add_u64 v[32:33], v[32:33], 0, v[158:159]
	global_load_dwordx2 v[34:35], v[32:33], off
	s_waitcnt vmcnt(0)
	v_cvt_f32_ubyte3_e32 v39, v34
	v_cvt_f32_ubyte2_e32 v38, v34
	v_cvt_f32_ubyte1_e32 v41, v34
	v_cvt_f32_ubyte0_e32 v40, v34
	v_pk_mul_f32 v[40:41], v[40:41], s[74:75] op_sel_hi:[1,0]
	v_pk_mul_f32 v[38:39], v[38:39], s[74:75] op_sel_hi:[1,0]
	v_pk_mul_f32 v[28:29], v[28:29], v[40:41]
	v_pk_mul_f32 v[30:31], v[30:31], v[38:39]
	global_store_dwordx4 v[36:37], v[28:31], off sc1
	s_nop 1
	v_cvt_f32_ubyte3_e32 v29, v35
	v_cvt_f32_ubyte2_e32 v28, v35
	v_cvt_f32_ubyte1_e32 v31, v35
	v_cvt_f32_ubyte0_e32 v30, v35
	v_pk_mul_f32 v[30:31], v[30:31], s[74:75] op_sel_hi:[1,0]
	v_pk_mul_f32 v[28:29], v[28:29], s[74:75] op_sel_hi:[1,0]
	v_pk_mul_f32 v[24:25], v[24:25], v[30:31]
	v_pk_mul_f32 v[26:27], v[26:27], v[28:29]
	global_store_dwordx4 v[36:37], v[24:27], off offset:16 sc1
	global_load_dwordx2 v[24:25], v[32:33], off offset:128
	s_waitcnt vmcnt(0)
	v_cvt_f32_ubyte1_e32 v29, v24
	v_cvt_f32_ubyte3_e32 v27, v24
	v_cvt_f32_ubyte2_e32 v26, v24
	v_cvt_f32_ubyte0_e32 v28, v24
	v_pk_mul_f32 v[28:29], v[28:29], s[74:75] op_sel_hi:[1,0]
	v_pk_mul_f32 v[26:27], v[26:27], s[74:75] op_sel_hi:[1,0]
	v_pk_mul_f32 v[20:21], v[20:21], v[28:29]
	v_pk_mul_f32 v[22:23], v[22:23], v[26:27]
	global_store_dwordx4 v[36:37], v[20:23], off offset:512 sc1
	s_nop 1
	v_cvt_f32_ubyte3_e32 v21, v25
	v_cvt_f32_ubyte2_e32 v20, v25
	v_cvt_f32_ubyte1_e32 v23, v25
	v_cvt_f32_ubyte0_e32 v22, v25
	v_pk_mul_f32 v[22:23], v[22:23], s[74:75] op_sel_hi:[1,0]
	v_pk_mul_f32 v[20:21], v[20:21], s[74:75] op_sel_hi:[1,0]
	v_pk_mul_f32 v[16:17], v[16:17], v[22:23]
	v_pk_mul_f32 v[18:19], v[18:19], v[20:21]
	global_store_dwordx4 v[36:37], v[16:19], off offset:528 sc1
	v_lshl_add_u64 v[20:21], s[8:9], 0, v[144:145]
	v_lshl_add_u64 v[20:21], v[20:21], 0, v[64:65]
	v_lshl_add_u64 v[16:17], v[152:153], 0, s[86:87]
	v_lshl_add_u64 v[16:17], v[16:17], 0, v[158:159]
	global_load_dwordx2 v[18:19], v[16:17], off
	s_waitcnt vmcnt(0)
	v_cvt_f32_ubyte3_e32 v23, v18
	v_cvt_f32_ubyte2_e32 v22, v18
	v_cvt_f32_ubyte1_e32 v25, v18
	v_cvt_f32_ubyte0_e32 v24, v18
	v_pk_mul_f32 v[24:25], v[24:25], s[74:75] op_sel_hi:[1,0]
	v_pk_mul_f32 v[22:23], v[22:23], s[74:75] op_sel_hi:[1,0]
	v_pk_mul_f32 v[12:13], v[12:13], v[24:25]
	v_pk_mul_f32 v[14:15], v[14:15], v[22:23]
	global_store_dwordx4 v[20:21], v[12:15], off sc1
	s_nop 1
	v_cvt_f32_ubyte3_e32 v13, v19
	v_cvt_f32_ubyte2_e32 v12, v19
	v_cvt_f32_ubyte1_e32 v15, v19
	v_cvt_f32_ubyte0_e32 v14, v19
	v_pk_mul_f32 v[14:15], v[14:15], s[74:75] op_sel_hi:[1,0]
	v_pk_mul_f32 v[12:13], v[12:13], s[74:75] op_sel_hi:[1,0]
	v_pk_mul_f32 v[8:9], v[8:9], v[14:15]
	v_pk_mul_f32 v[10:11], v[10:11], v[12:13]
	global_store_dwordx4 v[20:21], v[8:11], off offset:16 sc1
	global_load_dwordx2 v[8:9], v[16:17], off offset:128
	s_waitcnt vmcnt(0)
	v_cvt_f32_ubyte1_e32 v13, v8
	v_cvt_f32_ubyte3_e32 v11, v8
	v_cvt_f32_ubyte2_e32 v10, v8
	v_cvt_f32_ubyte0_e32 v12, v8
	v_pk_mul_f32 v[12:13], v[12:13], s[74:75] op_sel_hi:[1,0]
	v_pk_mul_f32 v[10:11], v[10:11], s[74:75] op_sel_hi:[1,0]
	v_pk_mul_f32 v[4:5], v[4:5], v[12:13]
	v_pk_mul_f32 v[6:7], v[6:7], v[10:11]
	global_store_dwordx4 v[20:21], v[4:7], off offset:512 sc1
	s_nop 1
	v_cvt_f32_ubyte3_e32 v5, v9
	v_cvt_f32_ubyte2_e32 v4, v9
	v_cvt_f32_ubyte1_e32 v7, v9
	v_cvt_f32_ubyte0_e32 v6, v9
	v_pk_mul_f32 v[6:7], v[6:7], s[74:75] op_sel_hi:[1,0]
	v_pk_mul_f32 v[4:5], v[4:5], s[74:75] op_sel_hi:[1,0]
	v_pk_mul_f32 v[0:1], v[0:1], v[6:7]
	v_pk_mul_f32 v[2:3], v[2:3], v[4:5]
	global_store_dwordx4 v[20:21], v[0:3], off offset:528 sc1
	s_waitcnt vmcnt(0)
	s_barrier
	s_and_saveexec_b64 s[8:9], s[18:19]
	s_cbranch_execz .LBB0_695
	s_lshl_b32 s14, s89, 6
	s_ashr_i32 s15, s14, 31
	s_lshl_b64 s[14:15], s[14:15], 2
	s_add_u32 s14, s75, s14
	s_addc_u32 s15, s21, s15
	s_waitcnt vmcnt(0)
	s_waitcnt vmcnt(0)
	v_mov_b64_e32 v[0:1], s[14:15]
	flat_atomic_add v0, v[0:1], v174 sc0
	s_waitcnt vmcnt(0) lgkmcnt(0)
	v_cmp_eq_u32_e32 vcc, 11, v0
	s_nop 1
	v_cndmask_b32_e64 v0, 0, 1, vcc
	ds_write_b32 v131, v0

.LBB0_816:
	s_lshl_b64 s[10:11], s[2:3], 20
	s_add_u32 s10, s12, s10
	s_addc_u32 s11, s13, s11
	v_lshl_add_u64 v[64:65], s[10:11], 0, v[140:141]
	v_lshlrev_b64 v[66:67], 2, v[152:153]
	v_lshl_add_u64 v[64:65], v[64:65], 0, v[66:67]
	global_store_dwordx4 v[64:65], v[60:63], off sc1
	global_store_dwordx4 v[64:65], v[56:59], off offset:16 sc1
	global_store_dwordx4 v[64:65], v[36:39], off offset:512 sc1
	global_store_dwordx4 v[64:65], v[32:35], off offset:528 sc1
	s_nop 1
	v_lshl_add_u64 v[32:33], s[10:11], 0, v[142:143]
	v_lshl_add_u64 v[32:33], v[32:33], 0, v[66:67]
	global_store_dwordx4 v[32:33], v[52:55], off sc1
	global_store_dwordx4 v[32:33], v[48:51], off offset:16 sc1
	global_store_dwordx4 v[32:33], v[20:23], off offset:512 sc1
	global_store_dwordx4 v[32:33], v[16:19], off offset:528 sc1
	s_nop 1
	v_lshl_add_u64 v[16:17], s[10:11], 0, v[144:145]
	v_lshl_add_u64 v[16:17], v[16:17], 0, v[66:67]
	global_store_dwordx4 v[16:17], v[44:47], off sc1
	global_store_dwordx4 v[16:17], v[40:43], off offset:16 sc1
	global_store_dwordx4 v[16:17], v[12:15], off offset:512 sc1
	global_store_dwordx4 v[16:17], v[8:11], off offset:528 sc1
	s_nop 1
	v_lshl_add_u64 v[8:9], s[10:11], 0, v[146:147]
	v_lshl_add_u64 v[8:9], v[8:9], 0, v[66:67]
	global_store_dwordx4 v[8:9], v[28:31], off sc1
	global_store_dwordx4 v[8:9], v[24:27], off offset:16 sc1
	global_store_dwordx4 v[8:9], v[4:7], off offset:512 sc1
	global_store_dwordx4 v[8:9], v[0:3], off offset:528 sc1
	s_waitcnt vmcnt(0)
	s_waitcnt vmcnt(0)
	s_barrier
	s_and_saveexec_b64 s[10:11], s[18:19]
	s_cbranch_execz .LBB0_818
	s_lshl_b32 s14, s0, 6
	s_ashr_i32 s15, s14, 31
	s_lshl_b64 s[14:15], s[14:15], 2
	s_add_u32 s14, s36, s14
	s_addc_u32 s15, s37, s15
	s_waitcnt vmcnt(0)
	v_mov_b64_e32 v[0:1], s[14:15]
	flat_atomic_add v0, v[0:1], v158 sc0
	s_waitcnt vmcnt(0) lgkmcnt(0)
	ds_write_b32 v137, v0
	v_mov_b64_e32 v[2:3], s[14:15]

.LBB0_1080:
	s_lshl_b64 s[0:1], s[2:3], 20
	s_add_u32 s0, s16, s0
	s_addc_u32 s1, s17, s1
	v_lshl_add_u64 v[64:65], s[0:1], 0, v[140:141]
	v_lshlrev_b64 v[66:67], 2, v[152:153]
	v_lshl_add_u64 v[64:65], v[64:65], 0, v[66:67]
	global_store_dwordx4 v[64:65], v[60:63], off sc1
	global_store_dwordx4 v[64:65], v[56:59], off offset:16 sc1
	global_store_dwordx4 v[64:65], v[36:39], off offset:512 sc1
	global_store_dwordx4 v[64:65], v[32:35], off offset:528 sc1
	s_nop 1
	v_lshl_add_u64 v[32:33], s[0:1], 0, v[142:143]
	v_lshl_add_u64 v[32:33], v[32:33], 0, v[66:67]
	global_store_dwordx4 v[32:33], v[52:55], off sc1
	global_store_dwordx4 v[32:33], v[48:51], off offset:16 sc1
	global_store_dwordx4 v[32:33], v[20:23], off offset:512 sc1
	global_store_dwordx4 v[32:33], v[16:19], off offset:528 sc1
	s_nop 1
	v_lshl_add_u64 v[16:17], s[0:1], 0, v[144:145]
	v_lshl_add_u64 v[16:17], v[16:17], 0, v[66:67]
	global_store_dwordx4 v[16:17], v[44:47], off sc1
	global_store_dwordx4 v[16:17], v[40:43], off offset:16 sc1
	global_store_dwordx4 v[16:17], v[12:15], off offset:512 sc1
	global_store_dwordx4 v[16:17], v[8:11], off offset:528 sc1
	s_nop 1
	v_lshl_add_u64 v[8:9], s[0:1], 0, v[146:147]
	v_lshl_add_u64 v[8:9], v[8:9], 0, v[66:67]
	global_store_dwordx4 v[8:9], v[28:31], off sc1
	global_store_dwordx4 v[8:9], v[24:27], off offset:16 sc1
	global_store_dwordx4 v[8:9], v[4:7], off offset:512 sc1
	global_store_dwordx4 v[8:9], v[0:3], off offset:528 sc1
	s_waitcnt vmcnt(0)
	s_waitcnt vmcnt(0)
	s_barrier
	s_and_saveexec_b64 s[0:1], s[18:19]
	s_cbranch_execz .LBB0_1082
	s_lshl_b32 s8, s57, 6
	s_ashr_i32 s9, s8, 31
	s_lshl_b64 s[8:9], s[8:9], 2
	s_add_u32 s8, s42, s8
	s_addc_u32 s9, s43, s9
	s_waitcnt vmcnt(0)
	v_mov_b64_e32 v[0:1], s[8:9]
	flat_atomic_add v0, v[0:1], v158 sc0
	s_waitcnt vmcnt(0) lgkmcnt(0)
	ds_write_b32 v137, v0
	v_mov_b64_e32 v[2:3], s[8:9]

.LBB0_1520:
	s_and_b64 vcc, exec, s[8:9]
	s_cbranch_vccz .LBB0_1526
	v_lshl_add_u64 v[66:67], v[162:163], 0, v[174:175]
	global_load_dwordx2 v[68:69], v[66:67], off
	s_add_i32 s4, s4, s81
	s_lshl_b64 s[8:9], s[4:5], 20
	s_add_u32 s64, s10, s8
	s_addc_u32 s65, s11, s9
	v_lshl_add_u64 v[70:71], s[64:65], 0, v[154:155]
	v_lshlrev_b64 v[64:65], 2, v[174:175]
	v_lshl_add_u64 v[70:71], v[70:71], 0, v[64:65]
	s_waitcnt vmcnt(0)
	v_cvt_f32_ubyte3_e32 v73, v68
	v_cvt_f32_ubyte2_e32 v72, v68
	v_cvt_f32_ubyte1_e32 v75, v68
	v_cvt_f32_ubyte0_e32 v74, v68
	v_pk_mul_f32 v[74:75], v[74:75], s[36:37] op_sel_hi:[1,0]
	v_pk_mul_f32 v[72:73], v[72:73], s[36:37] op_sel_hi:[1,0]
	v_pk_mul_f32 v[60:61], v[60:61], v[74:75]
	v_pk_mul_f32 v[62:63], v[62:63], v[72:73]
	global_store_dwordx4 v[70:71], v[60:63], off sc1
	s_nop 1
	v_cvt_f32_ubyte3_e32 v61, v69
	v_cvt_f32_ubyte2_e32 v60, v69
	v_cvt_f32_ubyte1_e32 v63, v69
	v_cvt_f32_ubyte0_e32 v62, v69
	v_pk_mul_f32 v[62:63], v[62:63], s[36:37] op_sel_hi:[1,0]
	v_pk_mul_f32 v[60:61], v[60:61], s[36:37] op_sel_hi:[1,0]
	v_pk_mul_f32 v[56:57], v[56:57], v[62:63]
	v_pk_mul_f32 v[58:59], v[58:59], v[60:61]
	global_store_dwordx4 v[70:71], v[56:59], off offset:16 sc1
	global_load_dwordx2 v[56:57], v[66:67], off offset:128
	s_waitcnt vmcnt(0)
	v_cvt_f32_ubyte1_e32 v61, v56
	v_cvt_f32_ubyte3_e32 v59, v56
	v_cvt_f32_ubyte2_e32 v58, v56
	v_cvt_f32_ubyte0_e32 v60, v56
	v_pk_mul_f32 v[60:61], v[60:61], s[36:37] op_sel_hi:[1,0]
	v_pk_mul_f32 v[58:59], v[58:59], s[36:37] op_sel_hi:[1,0]
	v_pk_mul_f32 v[52:53], v[52:53], v[60:61]
	v_pk_mul_f32 v[54:55], v[54:55], v[58:59]
	global_store_dwordx4 v[70:71], v[52:55], off offset:512 sc1
	s_nop 1
	v_cvt_f32_ubyte3_e32 v53, v57
	v_cvt_f32_ubyte2_e32 v52, v57
	v_cvt_f32_ubyte1_e32 v55, v57
	v_cvt_f32_ubyte0_e32 v54, v57
	v_pk_mul_f32 v[54:55], v[54:55], s[36:37] op_sel_hi:[1,0]
	v_pk_mul_f32 v[52:53], v[52:53], s[36:37] op_sel_hi:[1,0]
	v_pk_mul_f32 v[48:49], v[48:49], v[54:55]
	v_pk_mul_f32 v[50:51], v[50:51], v[52:53]
	global_store_dwordx4 v[70:71], v[48:51], off offset:528 sc1
	v_lshl_add_u64 v[52:53], s[64:65], 0, v[156:157]
	v_lshl_add_u64 v[52:53], v[52:53], 0, v[64:65]
	v_lshl_add_u64 v[48:49], v[164:165], 0, v[174:175]
	global_load_dwordx2 v[50:51], v[48:49], off
	s_waitcnt vmcnt(0)
	v_cvt_f32_ubyte3_e32 v55, v50
	v_cvt_f32_ubyte2_e32 v54, v50
	v_cvt_f32_ubyte1_e32 v57, v50
	v_cvt_f32_ubyte0_e32 v56, v50
	v_pk_mul_f32 v[56:57], v[56:57], s[36:37] op_sel_hi:[1,0]
	v_pk_mul_f32 v[54:55], v[54:55], s[36:37] op_sel_hi:[1,0]
	v_pk_mul_f32 v[44:45], v[44:45], v[56:57]
	v_pk_mul_f32 v[46:47], v[46:47], v[54:55]
	global_store_dwordx4 v[52:53], v[44:47], off sc1
	s_nop 1
	v_cvt_f32_ubyte3_e32 v45, v51
	v_cvt_f32_ubyte2_e32 v44, v51
	v_cvt_f32_ubyte1_e32 v47, v51
	v_cvt_f32_ubyte0_e32 v46, v51
	v_pk_mul_f32 v[46:47], v[46:47], s[36:37] op_sel_hi:[1,0]
	v_pk_mul_f32 v[44:45], v[44:45], s[36:37] op_sel_hi:[1,0]
	v_pk_mul_f32 v[40:41], v[40:41], v[46:47]
	v_pk_mul_f32 v[42:43], v[42:43], v[44:45]
	global_store_dwordx4 v[52:53], v[40:43], off offset:16 sc1
	global_load_dwordx2 v[40:41], v[48:49], off offset:128
	s_waitcnt vmcnt(0)
	v_cvt_f32_ubyte1_e32 v45, v40
	v_cvt_f32_ubyte3_e32 v43, v40
	v_cvt_f32_ubyte2_e32 v42, v40
	v_cvt_f32_ubyte0_e32 v44, v40
	v_pk_mul_f32 v[44:45], v[44:45], s[36:37] op_sel_hi:[1,0]
	v_pk_mul_f32 v[42:43], v[42:43], s[36:37] op_sel_hi:[1,0]
	v_pk_mul_f32 v[36:37], v[36:37], v[44:45]
	v_pk_mul_f32 v[38:39], v[38:39], v[42:43]
	global_store_dwordx4 v[52:53], v[36:39], off offset:512 sc1
	s_nop 1
	v_cvt_f32_ubyte3_e32 v37, v41
	v_cvt_f32_ubyte2_e32 v36, v41
	v_cvt_f32_ubyte1_e32 v39, v41
	v_cvt_f32_ubyte0_e32 v38, v41
	v_pk_mul_f32 v[38:39], v[38:39], s[36:37] op_sel_hi:[1,0]
	v_pk_mul_f32 v[36:37], v[36:37], s[36:37] op_sel_hi:[1,0]
	v_pk_mul_f32 v[32:33], v[32:33], v[38:39]
	v_pk_mul_f32 v[34:35], v[34:35], v[36:37]
	global_store_dwordx4 v[52:53], v[32:35], off offset:528 sc1
	v_lshl_add_u64 v[36:37], s[64:65], 0, v[158:159]
	v_lshl_add_u64 v[36:37], v[36:37], 0, v[64:65]
	v_lshl_add_u64 v[32:33], v[166:167], 0, v[174:175]
	global_load_dwordx2 v[34:35], v[32:33], off
	s_waitcnt vmcnt(0)
	v_cvt_f32_ubyte3_e32 v39, v34
	v_cvt_f32_ubyte2_e32 v38, v34
	v_cvt_f32_ubyte1_e32 v41, v34
	v_cvt_f32_ubyte0_e32 v40, v34
	v_pk_mul_f32 v[40:41], v[40:41], s[36:37] op_sel_hi:[1,0]
	v_pk_mul_f32 v[38:39], v[38:39], s[36:37] op_sel_hi:[1,0]
	v_pk_mul_f32 v[28:29], v[28:29], v[40:41]
	v_pk_mul_f32 v[30:31], v[30:31], v[38:39]
	global_store_dwordx4 v[36:37], v[28:31], off sc1
	s_nop 1
	v_cvt_f32_ubyte3_e32 v29, v35
	v_cvt_f32_ubyte2_e32 v28, v35
	v_cvt_f32_ubyte1_e32 v31, v35
	v_cvt_f32_ubyte0_e32 v30, v35
	v_pk_mul_f32 v[30:31], v[30:31], s[36:37] op_sel_hi:[1,0]
	v_pk_mul_f32 v[28:29], v[28:29], s[36:37] op_sel_hi:[1,0]
	v_pk_mul_f32 v[24:25], v[24:25], v[30:31]
	v_pk_mul_f32 v[26:27], v[26:27], v[28:29]
	global_store_dwordx4 v[36:37], v[24:27], off offset:16 sc1
	global_load_dwordx2 v[24:25], v[32:33], off offset:128
	s_waitcnt vmcnt(0)
	v_cvt_f32_ubyte1_e32 v29, v24
	v_cvt_f32_ubyte3_e32 v27, v24
	v_cvt_f32_ubyte2_e32 v26, v24
	v_cvt_f32_ubyte0_e32 v28, v24
	v_pk_mul_f32 v[28:29], v[28:29], s[36:37] op_sel_hi:[1,0]
	v_pk_mul_f32 v[26:27], v[26:27], s[36:37] op_sel_hi:[1,0]
	v_pk_mul_f32 v[20:21], v[20:21], v[28:29]
	v_pk_mul_f32 v[22:23], v[22:23], v[26:27]
	global_store_dwordx4 v[36:37], v[20:23], off offset:512 sc1
	s_nop 1
	v_cvt_f32_ubyte3_e32 v21, v25
	v_cvt_f32_ubyte2_e32 v20, v25
	v_cvt_f32_ubyte1_e32 v23, v25
	v_cvt_f32_ubyte0_e32 v22, v25
	v_pk_mul_f32 v[22:23], v[22:23], s[36:37] op_sel_hi:[1,0]
	v_pk_mul_f32 v[20:21], v[20:21], s[36:37] op_sel_hi:[1,0]
	v_pk_mul_f32 v[16:17], v[16:17], v[22:23]
	v_pk_mul_f32 v[18:19], v[18:19], v[20:21]
	global_store_dwordx4 v[36:37], v[16:19], off offset:528 sc1
	v_lshl_add_u64 v[20:21], s[64:65], 0, v[160:161]
	v_lshl_add_u64 v[20:21], v[20:21], 0, v[64:65]
	v_lshl_add_u64 v[16:17], v[168:169], 0, v[174:175]
	global_load_dwordx2 v[18:19], v[16:17], off
	s_waitcnt vmcnt(0)
	v_cvt_f32_ubyte3_e32 v23, v18
	v_cvt_f32_ubyte2_e32 v22, v18
	v_cvt_f32_ubyte1_e32 v25, v18
	v_cvt_f32_ubyte0_e32 v24, v18
	v_pk_mul_f32 v[24:25], v[24:25], s[36:37] op_sel_hi:[1,0]
	v_pk_mul_f32 v[22:23], v[22:23], s[36:37] op_sel_hi:[1,0]
	v_pk_mul_f32 v[12:13], v[12:13], v[24:25]
	v_pk_mul_f32 v[14:15], v[14:15], v[22:23]
	global_store_dwordx4 v[20:21], v[12:15], off sc1
	s_nop 1
	v_cvt_f32_ubyte3_e32 v13, v19
	v_cvt_f32_ubyte2_e32 v12, v19
	v_cvt_f32_ubyte1_e32 v15, v19
	v_cvt_f32_ubyte0_e32 v14, v19
	v_pk_mul_f32 v[14:15], v[14:15], s[36:37] op_sel_hi:[1,0]
	v_pk_mul_f32 v[12:13], v[12:13], s[36:37] op_sel_hi:[1,0]
	v_pk_mul_f32 v[8:9], v[8:9], v[14:15]
	v_pk_mul_f32 v[10:11], v[10:11], v[12:13]
	global_store_dwordx4 v[20:21], v[8:11], off offset:16 sc1
	global_load_dwordx2 v[8:9], v[16:17], off offset:128
	s_waitcnt vmcnt(0)
	v_cvt_f32_ubyte1_e32 v13, v8
	v_cvt_f32_ubyte3_e32 v11, v8
	v_cvt_f32_ubyte2_e32 v10, v8
	v_cvt_f32_ubyte0_e32 v12, v8
	v_pk_mul_f32 v[12:13], v[12:13], s[36:37] op_sel_hi:[1,0]
	v_pk_mul_f32 v[10:11], v[10:11], s[36:37] op_sel_hi:[1,0]
	v_pk_mul_f32 v[4:5], v[4:5], v[12:13]
	v_pk_mul_f32 v[6:7], v[6:7], v[10:11]
	global_store_dwordx4 v[20:21], v[4:7], off offset:512 sc1
	s_nop 1
	v_cvt_f32_ubyte3_e32 v5, v9
	v_cvt_f32_ubyte2_e32 v4, v9
	v_cvt_f32_ubyte1_e32 v7, v9
	v_cvt_f32_ubyte0_e32 v6, v9
	v_pk_mul_f32 v[6:7], v[6:7], s[36:37] op_sel_hi:[1,0]
	v_pk_mul_f32 v[4:5], v[4:5], s[36:37] op_sel_hi:[1,0]
	v_pk_mul_f32 v[0:1], v[0:1], v[6:7]
	v_pk_mul_f32 v[2:3], v[2:3], v[4:5]
	global_store_dwordx4 v[20:21], v[0:3], off offset:528 sc1
	s_waitcnt vmcnt(0)
	s_barrier
	s_and_saveexec_b64 s[8:9], s[18:19]
	s_cbranch_execz .LBB0_1523
	s_lshl_b32 s64, s84, 6
	s_ashr_i32 s65, s64, 31
	s_lshl_b64 s[64:65], s[64:65], 2
	s_add_u32 s64, s37, s64
	s_addc_u32 s65, s53, s65
	s_waitcnt vmcnt(0)
	s_waitcnt vmcnt(0)
	v_mov_b64_e32 v[0:1], s[64:65]
	flat_atomic_add v0, v[0:1], v182 sc0
	s_waitcnt vmcnt(0) lgkmcnt(0)
	ds_write_b32 v145, v0
	v_mov_b64_e32 v[2:3], s[64:65]

.LBB0_1627:
	s_and_b64 vcc, exec, s[4:5]
	s_cbranch_vccz .LBB0_1633
	s_lshl_b32 s8, s73, 11
	s_ashr_i32 s9, s8, 31
	v_lshl_add_u64 v[64:65], v[146:147], 0, s[8:9]
	v_lshl_add_u64 v[66:67], v[64:65], 0, v[158:159]
	global_load_dwordx2 v[68:69], v[66:67], off
	s_lshl_b32 s4, s73, 2
	s_add_i32 s4, s4, s72
	s_ashr_i32 s5, s4, 31
	s_lshl_b64 s[4:5], s[4:5], 20
	s_add_u32 s4, s10, s4
	s_addc_u32 s5, s11, s5
	v_lshlrev_b64 v[64:65], 2, v[158:159]
	v_lshl_add_u64 v[70:71], s[4:5], 0, v[138:139]
	v_lshl_add_u64 v[70:71], v[70:71], 0, v[64:65]
	s_waitcnt vmcnt(0)
	v_cvt_f32_ubyte3_e32 v73, v68
	v_cvt_f32_ubyte2_e32 v72, v68
	v_cvt_f32_ubyte1_e32 v75, v68
	v_cvt_f32_ubyte0_e32 v74, v68
	v_cvt_f32_ubyte3_e32 v77, v69
	v_cvt_f32_ubyte2_e32 v76, v69
	v_cvt_f32_ubyte1_e32 v79, v69
	v_cvt_f32_ubyte0_e32 v78, v69
	v_pk_mul_f32 v[68:69], v[74:75], s[36:37] op_sel_hi:[1,0]
	v_pk_mul_f32 v[72:73], v[72:73], s[36:37] op_sel_hi:[1,0]
	v_pk_mul_f32 v[74:75], v[78:79], s[36:37] op_sel_hi:[1,0]
	v_pk_mul_f32 v[76:77], v[76:77], s[36:37] op_sel_hi:[1,0]
	v_pk_mul_f32 v[62:63], v[62:63], v[72:73]
	v_pk_mul_f32 v[60:61], v[60:61], v[68:69]
	v_pk_mul_f32 v[58:59], v[58:59], v[76:77]
	v_pk_mul_f32 v[56:57], v[56:57], v[74:75]
	global_store_dwordx4 v[70:71], v[60:63], off sc1
	global_store_dwordx4 v[70:71], v[56:59], off offset:16 sc1
	global_load_dwordx2 v[56:57], v[66:67], off offset:128
	s_waitcnt vmcnt(0)
	v_cvt_f32_ubyte3_e32 v61, v56
	v_cvt_f32_ubyte2_e32 v60, v56
	v_cvt_f32_ubyte1_e32 v63, v56
	v_cvt_f32_ubyte0_e32 v62, v56
	v_cvt_f32_ubyte3_e32 v67, v57
	v_cvt_f32_ubyte2_e32 v66, v57
	v_cvt_f32_ubyte1_e32 v69, v57
	v_cvt_f32_ubyte0_e32 v68, v57
	v_pk_mul_f32 v[56:57], v[62:63], s[36:37] op_sel_hi:[1,0]
	v_pk_mul_f32 v[60:61], v[60:61], s[36:37] op_sel_hi:[1,0]
	v_lshl_add_u64 v[58:59], v[148:149], 0, s[8:9]
	v_pk_mul_f32 v[62:63], v[68:69], s[36:37] op_sel_hi:[1,0]
	v_pk_mul_f32 v[66:67], v[66:67], s[36:37] op_sel_hi:[1,0]
	v_pk_mul_f32 v[54:55], v[54:55], v[60:61]
	v_pk_mul_f32 v[52:53], v[52:53], v[56:57]
	v_lshl_add_u64 v[58:59], v[58:59], 0, v[158:159]
	v_pk_mul_f32 v[50:51], v[50:51], v[66:67]
	v_pk_mul_f32 v[48:49], v[48:49], v[62:63]
	global_store_dwordx4 v[70:71], v[52:55], off offset:512 sc1
	global_store_dwordx4 v[70:71], v[48:51], off offset:528 sc1
	global_load_dwordx2 v[48:49], v[58:59], off
	s_waitcnt vmcnt(0)
	v_cvt_f32_ubyte3_e32 v53, v48
	v_cvt_f32_ubyte2_e32 v52, v48
	v_cvt_f32_ubyte1_e32 v55, v48
	v_cvt_f32_ubyte0_e32 v54, v48
	v_lshl_add_u64 v[50:51], s[4:5], 0, v[140:141]
	v_cvt_f32_ubyte3_e32 v57, v49
	v_cvt_f32_ubyte2_e32 v56, v49
	v_cvt_f32_ubyte1_e32 v61, v49
	v_cvt_f32_ubyte0_e32 v60, v49
	v_pk_mul_f32 v[48:49], v[54:55], s[36:37] op_sel_hi:[1,0]
	v_pk_mul_f32 v[52:53], v[52:53], s[36:37] op_sel_hi:[1,0]
	v_lshl_add_u64 v[50:51], v[50:51], 0, v[64:65]
	v_pk_mul_f32 v[54:55], v[60:61], s[36:37] op_sel_hi:[1,0]
	v_pk_mul_f32 v[56:57], v[56:57], s[36:37] op_sel_hi:[1,0]
	v_pk_mul_f32 v[46:47], v[46:47], v[52:53]
	v_pk_mul_f32 v[44:45], v[44:45], v[48:49]
	v_pk_mul_f32 v[42:43], v[42:43], v[56:57]
	v_pk_mul_f32 v[40:41], v[40:41], v[54:55]
	global_store_dwordx4 v[50:51], v[44:47], off sc1
	global_store_dwordx4 v[50:51], v[40:43], off offset:16 sc1
	global_load_dwordx2 v[40:41], v[58:59], off offset:128
	s_waitcnt vmcnt(0)
	v_cvt_f32_ubyte3_e32 v45, v40
	v_cvt_f32_ubyte2_e32 v44, v40
	v_cvt_f32_ubyte1_e32 v47, v40
	v_cvt_f32_ubyte0_e32 v46, v40
	v_cvt_f32_ubyte3_e32 v49, v41
	v_cvt_f32_ubyte2_e32 v48, v41
	v_cvt_f32_ubyte1_e32 v53, v41
	v_cvt_f32_ubyte0_e32 v52, v41
	v_pk_mul_f32 v[40:41], v[46:47], s[36:37] op_sel_hi:[1,0]
	v_pk_mul_f32 v[44:45], v[44:45], s[36:37] op_sel_hi:[1,0]
	v_lshl_add_u64 v[42:43], v[150:151], 0, s[8:9]
	v_pk_mul_f32 v[46:47], v[52:53], s[36:37] op_sel_hi:[1,0]
	v_pk_mul_f32 v[48:49], v[48:49], s[36:37] op_sel_hi:[1,0]
	v_pk_mul_f32 v[38:39], v[38:39], v[44:45]
	v_pk_mul_f32 v[36:37], v[36:37], v[40:41]
	v_lshl_add_u64 v[42:43], v[42:43], 0, v[158:159]
	v_pk_mul_f32 v[34:35], v[34:35], v[48:49]
	v_pk_mul_f32 v[32:33], v[32:33], v[46:47]
	global_store_dwordx4 v[50:51], v[36:39], off offset:512 sc1
	global_store_dwordx4 v[50:51], v[32:35], off offset:528 sc1
	global_load_dwordx2 v[32:33], v[42:43], off
	s_waitcnt vmcnt(0)
	v_cvt_f32_ubyte3_e32 v37, v32
	v_cvt_f32_ubyte2_e32 v36, v32
	v_cvt_f32_ubyte1_e32 v39, v32
	v_cvt_f32_ubyte0_e32 v38, v32
	v_lshl_add_u64 v[34:35], s[4:5], 0, v[142:143]
	v_cvt_f32_ubyte3_e32 v41, v33
	v_cvt_f32_ubyte2_e32 v40, v33
	v_cvt_f32_ubyte1_e32 v45, v33
	v_cvt_f32_ubyte0_e32 v44, v33
	v_pk_mul_f32 v[32:33], v[38:39], s[36:37] op_sel_hi:[1,0]
	v_pk_mul_f32 v[36:37], v[36:37], s[36:37] op_sel_hi:[1,0]
	v_lshl_add_u64 v[34:35], v[34:35], 0, v[64:65]
	v_pk_mul_f32 v[38:39], v[44:45], s[36:37] op_sel_hi:[1,0]
	v_pk_mul_f32 v[40:41], v[40:41], s[36:37] op_sel_hi:[1,0]
	v_pk_mul_f32 v[30:31], v[30:31], v[36:37]
	v_pk_mul_f32 v[28:29], v[28:29], v[32:33]
	v_pk_mul_f32 v[26:27], v[26:27], v[40:41]
	v_pk_mul_f32 v[24:25], v[24:25], v[38:39]
	global_store_dwordx4 v[34:35], v[28:31], off sc1
	global_store_dwordx4 v[34:35], v[24:27], off offset:16 sc1
	global_load_dwordx2 v[24:25], v[42:43], off offset:128
	s_waitcnt vmcnt(0)
	v_cvt_f32_ubyte3_e32 v29, v24
	v_cvt_f32_ubyte2_e32 v28, v24
	v_cvt_f32_ubyte1_e32 v31, v24
	v_cvt_f32_ubyte0_e32 v30, v24
	v_cvt_f32_ubyte3_e32 v33, v25
	v_cvt_f32_ubyte2_e32 v32, v25
	v_cvt_f32_ubyte1_e32 v37, v25
	v_cvt_f32_ubyte0_e32 v36, v25
	v_pk_mul_f32 v[24:25], v[30:31], s[36:37] op_sel_hi:[1,0]
	v_pk_mul_f32 v[28:29], v[28:29], s[36:37] op_sel_hi:[1,0]
	v_lshl_add_u64 v[26:27], v[152:153], 0, s[8:9]
	v_pk_mul_f32 v[30:31], v[36:37], s[36:37] op_sel_hi:[1,0]
	v_pk_mul_f32 v[32:33], v[32:33], s[36:37] op_sel_hi:[1,0]
	v_pk_mul_f32 v[22:23], v[22:23], v[28:29]
	v_pk_mul_f32 v[20:21], v[20:21], v[24:25]
	v_lshl_add_u64 v[26:27], v[26:27], 0, v[158:159]
	v_pk_mul_f32 v[18:19], v[18:19], v[32:33]
	v_pk_mul_f32 v[16:17], v[16:17], v[30:31]
	global_store_dwordx4 v[34:35], v[20:23], off offset:512 sc1
	global_store_dwordx4 v[34:35], v[16:19], off offset:528 sc1
	global_load_dwordx2 v[16:17], v[26:27], off
	s_waitcnt vmcnt(0)
	v_cvt_f32_ubyte3_e32 v21, v16
	v_cvt_f32_ubyte2_e32 v20, v16
	v_cvt_f32_ubyte1_e32 v23, v16
	v_cvt_f32_ubyte0_e32 v22, v16
	v_lshl_add_u64 v[18:19], s[4:5], 0, v[144:145]
	v_cvt_f32_ubyte3_e32 v25, v17
	v_cvt_f32_ubyte2_e32 v24, v17
	v_cvt_f32_ubyte1_e32 v29, v17
	v_cvt_f32_ubyte0_e32 v28, v17
	v_pk_mul_f32 v[16:17], v[22:23], s[36:37] op_sel_hi:[1,0]
	v_pk_mul_f32 v[20:21], v[20:21], s[36:37] op_sel_hi:[1,0]
	v_lshl_add_u64 v[18:19], v[18:19], 0, v[64:65]
	v_pk_mul_f32 v[22:23], v[28:29], s[36:37] op_sel_hi:[1,0]
	v_pk_mul_f32 v[24:25], v[24:25], s[36:37] op_sel_hi:[1,0]
	v_pk_mul_f32 v[14:15], v[14:15], v[20:21]
	v_pk_mul_f32 v[12:13], v[12:13], v[16:17]
	v_pk_mul_f32 v[10:11], v[10:11], v[24:25]
	v_pk_mul_f32 v[8:9], v[8:9], v[22:23]
	global_store_dwordx4 v[18:19], v[12:15], off sc1
	global_store_dwordx4 v[18:19], v[8:11], off offset:16 sc1
	global_load_dwordx2 v[8:9], v[26:27], off offset:128
	s_waitcnt vmcnt(0)
	v_cvt_f32_ubyte1_e32 v13, v8
	v_cvt_f32_ubyte3_e32 v11, v8
	v_cvt_f32_ubyte2_e32 v10, v8
	v_cvt_f32_ubyte0_e32 v12, v8
	v_cvt_f32_ubyte3_e32 v15, v9
	v_cvt_f32_ubyte2_e32 v14, v9
	v_cvt_f32_ubyte1_e32 v17, v9
	v_cvt_f32_ubyte0_e32 v16, v9
	v_pk_mul_f32 v[8:9], v[12:13], s[36:37] op_sel_hi:[1,0]
	v_pk_mul_f32 v[10:11], v[10:11], s[36:37] op_sel_hi:[1,0]
	v_pk_mul_f32 v[12:13], v[16:17], s[36:37] op_sel_hi:[1,0]
	v_pk_mul_f32 v[14:15], v[14:15], s[36:37] op_sel_hi:[1,0]
	v_pk_mul_f32 v[6:7], v[6:7], v[10:11]
	v_pk_mul_f32 v[4:5], v[4:5], v[8:9]
	v_pk_mul_f32 v[2:3], v[2:3], v[14:15]
	v_pk_mul_f32 v[0:1], v[0:1], v[12:13]
	global_store_dwordx4 v[18:19], v[4:7], off offset:512 sc1
	global_store_dwordx4 v[18:19], v[0:3], off offset:528 sc1
	s_waitcnt vmcnt(0)
	s_barrier
	s_and_saveexec_b64 s[4:5], s[18:19]
	s_cbranch_execz .LBB0_1630
	s_lshl_b32 s8, s67, 6
	s_ashr_i32 s9, s8, 31
	s_lshl_b64 s[8:9], s[8:9], 2
	s_add_u32 s8, s37, s8
	s_addc_u32 s9, s53, s9
	s_waitcnt vmcnt(0)
	s_waitcnt vmcnt(0)
	v_mov_b64_e32 v[0:1], s[8:9]
	flat_atomic_add v0, v[0:1], v174 sc0
	s_waitcnt vmcnt(0) lgkmcnt(0)
	v_cmp_eq_u32_e32 vcc, 11, v0
	s_nop 1
	v_cndmask_b32_e64 v0, 0, 1, vcc
	ds_write_b32 v131, v0

.LBB0_1749:
	s_lshl_b64 s[4:5], s[6:7], 20
	s_add_u32 s4, s14, s4
	s_addc_u32 s5, s15, s5
	v_lshl_add_u64 v[64:65], s[4:5], 0, v[140:141]
	v_lshlrev_b64 v[66:67], 2, v[152:153]
	v_lshl_add_u64 v[64:65], v[64:65], 0, v[66:67]
	global_store_dwordx4 v[64:65], v[60:63], off sc1
	global_store_dwordx4 v[64:65], v[56:59], off offset:16 sc1
	global_store_dwordx4 v[64:65], v[36:39], off offset:512 sc1
	global_store_dwordx4 v[64:65], v[32:35], off offset:528 sc1
	s_nop 1
	v_lshl_add_u64 v[32:33], s[4:5], 0, v[142:143]
	v_lshl_add_u64 v[32:33], v[32:33], 0, v[66:67]
	global_store_dwordx4 v[32:33], v[52:55], off sc1
	global_store_dwordx4 v[32:33], v[48:51], off offset:16 sc1
	global_store_dwordx4 v[32:33], v[20:23], off offset:512 sc1
	global_store_dwordx4 v[32:33], v[16:19], off offset:528 sc1
	s_nop 1
	v_lshl_add_u64 v[16:17], s[4:5], 0, v[144:145]
	v_lshl_add_u64 v[16:17], v[16:17], 0, v[66:67]
	global_store_dwordx4 v[16:17], v[44:47], off sc1
	global_store_dwordx4 v[16:17], v[40:43], off offset:16 sc1
	global_store_dwordx4 v[16:17], v[12:15], off offset:512 sc1
	global_store_dwordx4 v[16:17], v[8:11], off offset:528 sc1
	s_nop 1
	v_lshl_add_u64 v[8:9], s[4:5], 0, v[146:147]
	v_lshl_add_u64 v[8:9], v[8:9], 0, v[66:67]
	global_store_dwordx4 v[8:9], v[28:31], off sc1
	global_store_dwordx4 v[8:9], v[24:27], off offset:16 sc1
	global_store_dwordx4 v[8:9], v[4:7], off offset:512 sc1
	global_store_dwordx4 v[8:9], v[0:3], off offset:528 sc1
	s_waitcnt vmcnt(0)
	s_waitcnt vmcnt(0)
	s_barrier
	s_and_saveexec_b64 s[4:5], s[18:19]
	s_cbranch_execz .LBB0_1751
	s_lshl_b32 s8, s0, 6
	s_ashr_i32 s9, s8, 31
	s_lshl_b64 s[8:9], s[8:9], 2
	s_add_u32 s8, s57, s8
	s_addc_u32 s9, s58, s9
	s_waitcnt vmcnt(0)
	v_mov_b64_e32 v[0:1], s[8:9]
	flat_atomic_add v0, v[0:1], v158 sc0
	s_waitcnt vmcnt(0) lgkmcnt(0)
	ds_write_b32 v137, v0
	v_mov_b64_e32 v[2:3], s[8:9]

.LBB0_1944:
	s_and_b64 vcc, exec, s[36:37]
	s_cbranch_vccz .LBB0_1950
	v_readlane_b32 s36, v254, 56
	v_readlane_b32 s37, v254, 57
	s_lshl_b64 s[36:37], s[36:37], 20
	s_add_u32 s36, s6, s36
	s_addc_u32 s37, s7, s37
	v_lshl_add_u64 v[0:1], s[36:37], 0, v[138:139]
	v_lshlrev_b64 v[2:3], 2, v[150:151]
	v_lshl_add_u64 v[0:1], v[0:1], 0, v[2:3]
	global_store_dwordx4 v[0:1], v[76:79], off sc1
	global_store_dwordx4 v[0:1], v[72:75], off offset:16 sc1
	global_store_dwordx4 v[0:1], v[44:47], off offset:512 sc1
	global_store_dwordx4 v[0:1], v[40:43], off offset:528 sc1
	v_lshl_add_u64 v[0:1], s[36:37], 0, v[140:141]
	v_lshl_add_u64 v[0:1], v[0:1], 0, v[2:3]
	global_store_dwordx4 v[0:1], v[68:71], off sc1
	global_store_dwordx4 v[0:1], v[64:67], off offset:16 sc1
	global_store_dwordx4 v[0:1], v[28:31], off offset:512 sc1
	global_store_dwordx4 v[0:1], v[24:27], off offset:528 sc1
	v_lshl_add_u64 v[0:1], s[36:37], 0, v[142:143]
	v_lshl_add_u64 v[0:1], v[0:1], 0, v[2:3]
	global_store_dwordx4 v[0:1], v[56:59], off sc1
	global_store_dwordx4 v[0:1], v[48:51], off offset:16 sc1
	global_store_dwordx4 v[0:1], v[20:23], off offset:512 sc1
	global_store_dwordx4 v[0:1], v[16:19], off offset:528 sc1
	v_lshl_add_u64 v[0:1], s[36:37], 0, v[144:145]
	v_lshl_add_u64 v[0:1], v[0:1], 0, v[2:3]
	global_store_dwordx4 v[0:1], v[36:39], off sc1
	global_store_dwordx4 v[0:1], v[32:35], off offset:16 sc1
	global_store_dwordx4 v[0:1], v[8:11], off offset:512 sc1
	global_store_dwordx4 v[0:1], v[4:7], off offset:528 sc1
	s_waitcnt vmcnt(0)
	s_waitcnt vmcnt(0)
	s_barrier
	s_and_saveexec_b64 s[36:37], s[18:19]
	s_cbranch_execz .LBB0_1947
	s_lshl_b32 s40, s89, 6
	s_ashr_i32 s41, s40, 31
	s_lshl_b64 s[40:41], s[40:41], 2
	s_add_u32 s40, s51, s40
	s_addc_u32 s41, s52, s41
	s_waitcnt vmcnt(0)
	v_mov_b64_e32 v[0:1], s[40:41]
	flat_atomic_add v0, v[0:1], v156 sc0
	s_waitcnt vmcnt(0) lgkmcnt(0)
	ds_write_b32 v131, v0
	v_mov_b64_e32 v[2:3], s[40:41]
